# P8 out-projection GEMM: first body peeled with C=0 MFMAs, accumulator zeroing removed
# speedup vs baseline: 1.0095x; 1.0007x over previous
; #define PG8_STAGE(bufoff, gbase, voff) do { _Pragma("unroll") for (int _i = 0; _i < 2; ++_i) \
;         __builtin_amdgcn_global_load_lds((const unsigned*)((const char*)(gbase) + (voff)[_i]), (LAS unsigned*)(lds + (bufoff) + ldsw + _i * 8192), 16, 0, 0); } while (0)
; #define PG8_LDA(dst, b, h) do { _Pragma("unroll") for (int m = 0; m < 4; ++m) _Pragma("unroll") for (int k = 0; k < 2; ++k) dst[m][k] = *(const LAS bf16x8*)(lds + PG8_SA(b, h) + aoff + m * 2048 + k * 1024); } while (0)
; #define PG8_LDB(dst, b, h) do { _Pragma("unroll") for (int n = 0; n < 2; ++n) _Pragma("unroll") for (int k = 0; k < 2; ++k) dst[n][k] = *(const LAS bf16x8*)(lds + PG8_SB(b, h) + boff + n * 2048 + k * 1024); } while (0)
; template <class Epi, bool AFTER = false>
; __device__ __forceinline__ void gemm_phase(LAS unsigned char* lds, const Gemm g, const StaticOrder& S, const Epi& E) {
;     ...
;         const bool has_next = S.next(ui + 1, nxt);
;         const char* nA = has_next ? (const char*)g.A + (size_t)nxt.pm * tstep : cA; const char* nB = has_next ? (const char*)g.Bt + (size_t)nxt.pn * tstep : cB;
;         for (int t = 0; t < nt; t += 2) {
;             const bool last = (t == nt - 2);
;             const char* a1 = cA + (size_t)(t + 1) * kstep;
;             const char* a2 = last ? nA : cA + (size_t)(t + 2) * kstep; const char* b2 = last ? nB : cB + (size_t)(t + 2) * kstep;
;             const char* a3 = a2 + kstep; const char* b3 = b2 + kstep;
;             PG8_LDB(B0, 0, 0); PG8_SCHED; PG8_LDA(At, 0, 0); PG8_STAGE(PG8_SA(1, 1), a1 + hstep, voffA);
;             PG8_WAIT_L(8); PG8_BAR; PG8_WAIT_L(0); PG8_MMA(0, 0, At, B0); PG8_BAR; PG8_SCHED;
;             PG8_LDB(B1, 0, 1); PG8_STAGE(PG8_SB(0, 0), b2, voffB);
;             PG8_BAR; PG8_WAIT_L(0); PG8_MMA(0, 1, At, B1); PG8_BAR;
;             PG8_LDA(At, 0, 1); PG8_STAGE(PG8_SA(0, 0), a2, voffA);
;             PG8_BAR; PG8_WAIT_L(0); PG8_MMA(1, 0, At, B0); PG8_BAR; PG8_SCHED;
;             PG8_STAGE(PG8_SB(0, 1), b2 + hstep, voffB);
;             PG8_WAIT_V(6); PG8_BAR; PG8_MMA(1, 1, At, B1); PG8_BAR;
;     ...
; #pragma unroll
;         for (int a = 0; a < 2; ++a)
; #pragma unroll
;             for (int b = 0; b < 2; ++b)
; #pragma unroll
;                 for (int m = 0; m < 4; ++m)
; #pragma unroll
;                     for (int n = 0; n < 2; ++n) acc[a][b][m][n] = (f32x4){0.f, 0.f, 0.f, 0.f};
.LBB0_846:
	s_ashr_i32 s23, s22, 31
	v_cmp_lt_i64_e32 vcc, s[24:25], v[140:141]
	s_lshl_b64 s[24:25], s[22:23], 19
	s_add_u32 s24, s33, s24
	s_addc_u32 s25, s36, s25
	s_and_b64 s[26:27], vcc, exec
	s_cselect_b32 s23, s25, s29
	s_cselect_b32 s56, s24, s28
	s_ashr_i32 s21, s20, 31
	s_lshl_b64 s[26:27], s[20:21], 19
	s_add_u32 s26, s37, s26
	s_addc_u32 s27, s38, s27
	s_and_b64 s[34:35], vcc, exec
	s_cselect_b32 s21, s27, s31
	s_cselect_b32 s57, s26, s30
	s_add_u32 s28, s28, 0x40080
	s_addc_u32 s29, s29, 0
	s_add_u32 s58, s30, 0x100
	s_addc_u32 s59, s31, 0
	s_mov_b32 s60, -2
	ds_read_b128 v[150:153], v147
	ds_read_b128 v[154:157], v147 offset:1024
	ds_read_b128 v[158:161], v147 offset:2048
	ds_read_b128 v[162:165], v147 offset:3072
	s_add_u32 s30, s28, 0xfffc0080
	s_addc_u32 s31, s29, -1
	s_cmp_eq_u32 s60, 12
	s_cselect_b32 s35, s23, s31
	s_cselect_b32 s34, s56, s30
	s_cselect_b32 s31, s21, s59
	s_cselect_b32 s30, s57, s58
	v_lshl_add_u64 v[198:199], s[28:29], 0, v[136:137]
	s_add_i32 m0, s9, 0xc000
	ds_read_b128 v[166:169], v148
	ds_read_b128 v[170:173], v148 offset:1024
	ds_read_b128 v[174:177], v148 offset:2048
	ds_read_b128 v[178:181], v148 offset:3072
	ds_read_b128 v[182:185], v148 offset:4096
	ds_read_b128 v[186:189], v148 offset:5120
	ds_read_b128 v[190:193], v148 offset:6144
	ds_read_b128 v[194:197], v148 offset:7168
	global_load_lds_dwordx4 v[198:199], off
	v_lshl_add_u64 v[198:199], s[28:29], 0, v[138:139]
	s_add_i32 m0, s9, 0xe000
	s_nop 0
	global_load_lds_dwordx4 v[198:199], off
	s_waitcnt lgkmcnt(8)
	s_barrier
	s_waitcnt lgkmcnt(0)
	s_setprio 1
	s_waitcnt lgkmcnt(0)
	v_mfma_f32_16x16x32_bf16 v[124:127], v[150:153], v[166:169], 0
	v_mfma_f32_16x16x32_bf16 v[120:123], v[158:161], v[166:169], 0
	v_mfma_f32_16x16x32_bf16 v[116:119], v[150:153], v[174:177], 0
	v_mfma_f32_16x16x32_bf16 v[112:115], v[158:161], v[174:177], 0
	v_mfma_f32_16x16x32_bf16 v[100:103], v[150:153], v[182:185], 0
	v_mfma_f32_16x16x32_bf16 v[96:99], v[158:161], v[182:185], 0
	v_mfma_f32_16x16x32_bf16 v[84:87], v[150:153], v[190:193], 0
	v_mfma_f32_16x16x32_bf16 v[80:83], v[158:161], v[190:193], 0
	v_mfma_f32_16x16x32_bf16 v[124:127], v[154:157], v[170:173], v[124:127]
	v_mfma_f32_16x16x32_bf16 v[120:123], v[162:165], v[170:173], v[120:123]
	v_mfma_f32_16x16x32_bf16 v[116:119], v[154:157], v[178:181], v[116:119]
	v_mfma_f32_16x16x32_bf16 v[112:115], v[162:165], v[178:181], v[112:115]
	v_mfma_f32_16x16x32_bf16 v[100:103], v[154:157], v[186:189], v[100:103]
	v_mfma_f32_16x16x32_bf16 v[96:99], v[162:165], v[186:189], v[96:99]
	v_mfma_f32_16x16x32_bf16 v[84:87], v[154:157], v[194:197], v[84:87]
	v_mfma_f32_16x16x32_bf16 v[80:83], v[162:165], v[194:197], v[80:83]
	s_setprio 0
	s_barrier
	s_add_i32 s61, s50, s41
	v_lshl_add_u64 v[210:211], s[30:31], 0, v[130:131]
	s_mov_b32 m0, s61
	ds_read_b128 v[198:201], v149
	ds_read_b128 v[202:205], v149 offset:1024
	ds_read_b128 v[206:209], v149 offset:2048
	ds_read_b128 v[214:217], v149 offset:3072
	global_load_lds_dwordx4 v[210:211], off
	v_lshl_add_u64 v[218:219], s[30:31], 0, v[134:135]
	s_add_i32 m0, s61, 0x2000
	s_nop 0
	global_load_lds_dwordx4 v[218:219], off
	s_barrier
	s_waitcnt lgkmcnt(0)
	s_setprio 1
	s_waitcnt lgkmcnt(0)
	v_mfma_f32_16x16x32_bf16 v[108:111], v[198:201], v[166:169], 0
	v_mfma_f32_16x16x32_bf16 v[104:107], v[206:209], v[166:169], 0
	v_mfma_f32_16x16x32_bf16 v[92:95], v[198:201], v[174:177], 0
	v_mfma_f32_16x16x32_bf16 v[88:91], v[206:209], v[174:177], 0
	v_mfma_f32_16x16x32_bf16 v[76:79], v[198:201], v[182:185], 0
	v_mfma_f32_16x16x32_bf16 v[72:75], v[206:209], v[182:185], 0
	v_mfma_f32_16x16x32_bf16 v[68:71], v[198:201], v[190:193], 0
	v_mfma_f32_16x16x32_bf16 v[64:67], v[206:209], v[190:193], 0
	v_mfma_f32_16x16x32_bf16 v[108:111], v[202:205], v[170:173], v[108:111]
	v_mfma_f32_16x16x32_bf16 v[104:107], v[214:217], v[170:173], v[104:107]
	v_mfma_f32_16x16x32_bf16 v[92:95], v[202:205], v[178:181], v[92:95]
	v_mfma_f32_16x16x32_bf16 v[88:91], v[214:217], v[178:181], v[88:91]
	v_mfma_f32_16x16x32_bf16 v[76:79], v[202:205], v[186:189], v[76:79]
	v_mfma_f32_16x16x32_bf16 v[72:75], v[214:217], v[186:189], v[72:75]
	v_mfma_f32_16x16x32_bf16 v[68:71], v[202:205], v[194:197], v[68:71]
	v_mfma_f32_16x16x32_bf16 v[64:67], v[214:217], v[194:197], v[64:67]
	s_setprio 0
	s_mov_b32 m0, s9
	v_lshl_add_u64 v[220:221], s[34:35], 0, v[128:129]
	s_barrier
	ds_read_b128 v[166:169], v148 offset:16384
	ds_read_b128 v[170:173], v148 offset:17408
	ds_read_b128 v[174:177], v148 offset:18432
	ds_read_b128 v[178:181], v148 offset:19456
	ds_read_b128 v[182:185], v148 offset:20480
	ds_read_b128 v[186:189], v148 offset:21504
	ds_read_b128 v[190:193], v148 offset:22528
	ds_read_b128 v[194:197], v148 offset:23552
	global_load_lds_dwordx4 v[220:221], off
	v_lshl_add_u64 v[222:223], s[34:35], 0, v[132:133]
	s_mov_b32 m0, s42
	s_nop 0
	global_load_lds_dwordx4 v[222:223], off
	s_barrier
	s_waitcnt lgkmcnt(0)
	s_setprio 1
	s_waitcnt lgkmcnt(0)
	v_mfma_f32_16x16x32_bf16 v[60:63], v[150:153], v[166:169], 0
	v_mfma_f32_16x16x32_bf16 v[56:59], v[158:161], v[166:169], 0
	v_mfma_f32_16x16x32_bf16 v[52:55], v[150:153], v[174:177], 0
	v_mfma_f32_16x16x32_bf16 v[48:51], v[158:161], v[174:177], 0
	v_mfma_f32_16x16x32_bf16 v[40:43], v[150:153], v[182:185], 0
	v_mfma_f32_16x16x32_bf16 v[32:35], v[158:161], v[182:185], 0
	v_mfma_f32_16x16x32_bf16 v[24:27], v[150:153], v[190:193], 0
	v_mfma_f32_16x16x32_bf16 v[16:19], v[158:161], v[190:193], 0
	v_mfma_f32_16x16x32_bf16 v[60:63], v[154:157], v[170:173], v[60:63]
	v_mfma_f32_16x16x32_bf16 v[56:59], v[162:165], v[170:173], v[56:59]
	v_mfma_f32_16x16x32_bf16 v[52:55], v[154:157], v[178:181], v[52:55]
	v_mfma_f32_16x16x32_bf16 v[48:51], v[162:165], v[178:181], v[48:51]
	v_mfma_f32_16x16x32_bf16 v[40:43], v[154:157], v[186:189], v[40:43]
	v_mfma_f32_16x16x32_bf16 v[32:35], v[162:165], v[186:189], v[32:35]
	v_mfma_f32_16x16x32_bf16 v[24:27], v[154:157], v[194:197], v[24:27]
	v_mfma_f32_16x16x32_bf16 v[16:19], v[162:165], v[194:197], v[16:19]
	s_setprio 0
	s_barrier
; #define PG8_STAGE(bufoff, gbase, voff) do { _Pragma("unroll") for (int _i = 0; _i < 2; ++_i) \
;         __builtin_amdgcn_global_load_lds((const unsigned*)((const char*)(gbase) + (voff)[_i]), (LAS unsigned*)(lds + (bufoff) + ldsw + _i * 8192), 16, 0, 0); } while (0)
; #define PG8_LDA(dst, b, h) do { _Pragma("unroll") for (int m = 0; m < 4; ++m) _Pragma("unroll") for (int k = 0; k < 2; ++k) dst[m][k] = *(const LAS bf16x8*)(lds + PG8_SA(b, h) + aoff + m * 2048 + k * 1024); } while (0)
; #define PG8_LDB(dst, b, h) do { _Pragma("unroll") for (int n = 0; n < 2; ++n) _Pragma("unroll") for (int k = 0; k < 2; ++k) dst[n][k] = *(const LAS bf16x8*)(lds + PG8_SB(b, h) + boff + n * 2048 + k * 1024); } while (0)
; #define PG8_MMA(ai, bj, At, Bt) do { __builtin_amdgcn_s_setprio(1); _Pragma("unroll") for (int m = 0; m < 4; ++m) _Pragma("unroll") for (int n = 0; n < 2; ++n) _Pragma("unroll") for (int k = 0; k < 2; ++k) \
;         acc[ai][bj][m][n] = __builtin_amdgcn_mfma_f32_16x16x32_bf16(Bt[n][k], At[m][k], acc[ai][bj][m][n], 0, 0, 0); __builtin_amdgcn_s_setprio(0); } while (0)
; #define PG8_WAIT_V(n) asm volatile("s_waitcnt vmcnt(" #n ")" ::: "memory")
; #define PG8_WAIT_L(n) asm volatile("s_waitcnt lgkmcnt(" #n ")" ::: "memory")
; #define PG8_BAR __builtin_amdgcn_s_barrier()
; #define PG8_SCHED __builtin_amdgcn_sched_barrier(0)
; #define PG8_LDA(dst, b, h) do { _Pragma("unroll") for (int m = 0; m < 4; ++m) _Pragma("unroll") for (int k = 0; k < 2; ++k) dst[m][k] = *(const LAS bf16x8*)(lds + PG8_SA(b, h) + aoff + m * 2048 + k * 1024); } while (0)
; #define PG8_WAIT_V(n) asm volatile("s_waitcnt vmcnt(" #n ")" ::: "memory")
; #define PG8_BAR __builtin_amdgcn_s_barrier()
; template <class Epi, bool AFTER = false>
; __device__ __forceinline__ void gemm_phase(LAS unsigned char* lds, const Gemm g, const StaticOrder& S, const Epi& E) {
;     ...
;             PG8_STAGE(PG8_SB(0, 1), b2 + hstep, voffB);
;             PG8_WAIT_V(6); PG8_BAR; PG8_MMA(1, 1, At, B1); PG8_BAR;
;             PG8_LDB(B0, 1, 0); PG8_SCHED; PG8_LDA(At, 1, 0); PG8_STAGE(PG8_SA(0, 1), a2 + hstep, voffA);
;             PG8_WAIT_L(8); PG8_BAR; PG8_WAIT_L(0); PG8_MMA(0, 0, At, B0); PG8_BAR; PG8_SCHED;
;             PG8_LDB(B1, 1, 1); PG8_STAGE(PG8_SB(1, 0), b3, voffB);
;             PG8_BAR; PG8_WAIT_L(0); PG8_MMA(0, 1, At, B1); PG8_BAR;
;             PG8_LDA(At, 1, 1); PG8_STAGE(PG8_SA(1, 0), a3, voffA);
	s_add_u32 s62, s30, 0x40000
	s_addc_u32 s63, s31, 0
	s_add_i32 s61, s51, s41
	v_lshl_add_u64 v[150:151], s[62:63], 0, v[130:131]
	s_mov_b32 m0, s61
	s_nop 0
	global_load_lds_dwordx4 v[150:151], off
	v_lshl_add_u64 v[150:151], s[62:63], 0, v[134:135]
	s_add_i32 m0, s61, 0x2000
	s_nop 0
	global_load_lds_dwordx4 v[150:151], off
	s_waitcnt vmcnt(6)
	s_barrier
	s_setprio 1
	v_mfma_f32_16x16x32_bf16 v[44:47], v[198:201], v[166:169], 0
	v_mfma_f32_16x16x32_bf16 v[36:39], v[206:209], v[166:169], 0
	v_mfma_f32_16x16x32_bf16 v[28:31], v[198:201], v[174:177], 0
	v_mfma_f32_16x16x32_bf16 v[20:23], v[206:209], v[174:177], 0
	v_mfma_f32_16x16x32_bf16 v[12:15], v[198:201], v[182:185], 0
	v_mfma_f32_16x16x32_bf16 v[8:11], v[206:209], v[182:185], 0
	v_mfma_f32_16x16x32_bf16 v[4:7], v[198:201], v[190:193], 0
	v_mfma_f32_16x16x32_bf16 v[0:3], v[206:209], v[190:193], 0
	v_mfma_f32_16x16x32_bf16 v[44:47], v[202:205], v[170:173], v[44:47]
	v_mfma_f32_16x16x32_bf16 v[36:39], v[214:217], v[170:173], v[36:39]
	v_mfma_f32_16x16x32_bf16 v[28:31], v[202:205], v[178:181], v[28:31]
	v_mfma_f32_16x16x32_bf16 v[20:23], v[214:217], v[178:181], v[20:23]
	v_mfma_f32_16x16x32_bf16 v[12:15], v[202:205], v[186:189], v[12:15]
	v_mfma_f32_16x16x32_bf16 v[8:11], v[214:217], v[186:189], v[8:11]
	v_mfma_f32_16x16x32_bf16 v[4:7], v[202:205], v[194:197], v[4:7]
	v_mfma_f32_16x16x32_bf16 v[0:3], v[214:217], v[194:197], v[0:3]
	s_setprio 0
	s_add_i32 s61, 0, 0x18000
	v_add_u32_e32 v162, s61, v145
	s_barrier
	ds_read_b128 v[150:153], v162
	ds_read_b128 v[154:157], v162 offset:1024
	ds_read_b128 v[158:161], v162 offset:2048
	ds_read_b128 v[162:165], v162 offset:3072
	s_add_u32 s34, s34, 0x40000
	s_addc_u32 s35, s35, 0
	s_mov_b32 m0, s43
	v_lshl_add_u64 v[198:199], s[34:35], 0, v[128:129]
	ds_read_b128 v[166:169], v148 offset:32768
	ds_read_b128 v[170:173], v148 offset:33792
	ds_read_b128 v[174:177], v148 offset:34816
	ds_read_b128 v[178:181], v148 offset:35840
	ds_read_b128 v[182:185], v148 offset:36864
	ds_read_b128 v[186:189], v148 offset:37888
	ds_read_b128 v[190:193], v148 offset:38912
	ds_read_b128 v[194:197], v148 offset:39936
	global_load_lds_dwordx4 v[198:199], off
	v_lshl_add_u64 v[198:199], s[34:35], 0, v[132:133]
	s_mov_b32 m0, s44
	s_nop 0
	global_load_lds_dwordx4 v[198:199], off
	s_waitcnt lgkmcnt(8)
	s_barrier
	s_waitcnt lgkmcnt(0)
	s_setprio 1
	s_waitcnt lgkmcnt(0)
	v_mfma_f32_16x16x32_bf16 v[124:127], v[150:153], v[166:169], v[124:127]
	v_mfma_f32_16x16x32_bf16 v[120:123], v[158:161], v[166:169], v[120:123]
	v_mfma_f32_16x16x32_bf16 v[116:119], v[150:153], v[174:177], v[116:119]
	v_mfma_f32_16x16x32_bf16 v[112:115], v[158:161], v[174:177], v[112:115]
	v_mfma_f32_16x16x32_bf16 v[100:103], v[150:153], v[182:185], v[100:103]
	v_mfma_f32_16x16x32_bf16 v[96:99], v[158:161], v[182:185], v[96:99]
	v_mfma_f32_16x16x32_bf16 v[84:87], v[150:153], v[190:193], v[84:87]
	v_mfma_f32_16x16x32_bf16 v[80:83], v[158:161], v[190:193], v[80:83]
	v_mfma_f32_16x16x32_bf16 v[124:127], v[154:157], v[170:173], v[124:127]
	v_mfma_f32_16x16x32_bf16 v[120:123], v[162:165], v[170:173], v[120:123]
	v_mfma_f32_16x16x32_bf16 v[116:119], v[154:157], v[178:181], v[116:119]
	v_mfma_f32_16x16x32_bf16 v[112:115], v[162:165], v[178:181], v[112:115]
	v_mfma_f32_16x16x32_bf16 v[100:103], v[154:157], v[186:189], v[100:103]
	v_mfma_f32_16x16x32_bf16 v[96:99], v[162:165], v[186:189], v[96:99]
	v_mfma_f32_16x16x32_bf16 v[84:87], v[154:157], v[194:197], v[84:87]
	v_mfma_f32_16x16x32_bf16 v[80:83], v[162:165], v[194:197], v[80:83]
	s_setprio 0
	s_barrier
	s_add_i32 s34, 0, 0x1c000
	s_add_i32 s35, s61, s41
	v_add_u32_e32 v213, s34, v145
	v_lshl_add_u64 v[210:211], v[210:211], 0, s[10:11]
	s_mov_b32 m0, s35
	ds_read_b128 v[198:201], v213
	ds_read_b128 v[202:205], v213 offset:1024
	ds_read_b128 v[206:209], v213 offset:2048
	ds_read_b128 v[214:217], v213 offset:3072
	global_load_lds_dwordx4 v[210:211], off
	v_lshl_add_u64 v[210:211], v[218:219], 0, s[10:11]
	s_add_i32 m0, s35, 0x2000
	s_nop 0
	global_load_lds_dwordx4 v[210:211], off
	s_barrier
; #define PG8_STAGE(bufoff, gbase, voff) do { _Pragma("unroll") for (int _i = 0; _i < 2; ++_i) \
;         __builtin_amdgcn_global_load_lds((const unsigned*)((const char*)(gbase) + (voff)[_i]), (LAS unsigned*)(lds + (bufoff) + ldsw + _i * 8192), 16, 0, 0); } while (0)
; #define PG8_LDA(dst, b, h) do { _Pragma("unroll") for (int m = 0; m < 4; ++m) _Pragma("unroll") for (int k = 0; k < 2; ++k) dst[m][k] = *(const LAS bf16x8*)(lds + PG8_SA(b, h) + aoff + m * 2048 + k * 1024); } while (0)
; #define PG8_LDB(dst, b, h) do { _Pragma("unroll") for (int n = 0; n < 2; ++n) _Pragma("unroll") for (int k = 0; k < 2; ++k) dst[n][k] = *(const LAS bf16x8*)(lds + PG8_SB(b, h) + boff + n * 2048 + k * 1024); } while (0)
; #define PG8_MMA(ai, bj, At, Bt) do { __builtin_amdgcn_s_setprio(1); _Pragma("unroll") for (int m = 0; m < 4; ++m) _Pragma("unroll") for (int n = 0; n < 2; ++n) _Pragma("unroll") for (int k = 0; k < 2; ++k) \
;         acc[ai][bj][m][n] = __builtin_amdgcn_mfma_f32_16x16x32_bf16(Bt[n][k], At[m][k], acc[ai][bj][m][n], 0, 0, 0); __builtin_amdgcn_s_setprio(0); } while (0)
; #define PG8_WAIT_V(n) asm volatile("s_waitcnt vmcnt(" #n ")" ::: "memory")
; #define PG8_WAIT_L(n) asm volatile("s_waitcnt lgkmcnt(" #n ")" ::: "memory")
; #define PG8_BAR __builtin_amdgcn_s_barrier()
; #define PG8_SCHED __builtin_amdgcn_sched_barrier(0)
; #define PG8_LDA(dst, b, h) do { _Pragma("unroll") for (int m = 0; m < 4; ++m) _Pragma("unroll") for (int k = 0; k < 2; ++k) dst[m][k] = *(const LAS bf16x8*)(lds + PG8_SA(b, h) + aoff + m * 2048 + k * 1024); } while (0)
; #define PG8_WAIT_V(n) asm volatile("s_waitcnt vmcnt(" #n ")" ::: "memory")
; #define PG8_WAIT_L(n) asm volatile("s_waitcnt lgkmcnt(" #n ")" ::: "memory")
; template <class Epi, bool AFTER = false>
; __device__ __forceinline__ void gemm_phase(LAS unsigned char* lds, const Gemm g, const StaticOrder& S, const Epi& E) {
;     ...
;             PG8_WAIT_L(8); PG8_BAR; PG8_WAIT_L(0); PG8_MMA(0, 0, At, B0); PG8_BAR; PG8_SCHED;
;             PG8_LDB(B1, 1, 1); PG8_STAGE(PG8_SB(1, 0), b3, voffB);
;             PG8_BAR; PG8_WAIT_L(0); PG8_MMA(0, 1, At, B1); PG8_BAR;
;             PG8_LDA(At, 1, 1); PG8_STAGE(PG8_SA(1, 0), a3, voffA);
;             PG8_BAR; PG8_WAIT_L(0); PG8_MMA(1, 0, At, B0); PG8_BAR; PG8_SCHED;
;             PG8_STAGE(PG8_SB(1, 1), b3 + hstep, voffB);
;             PG8_WAIT_V(6); PG8_BAR; PG8_MMA(1, 1, At, B1); PG8_BAR;
	s_waitcnt lgkmcnt(0)
	s_setprio 1
	s_waitcnt lgkmcnt(0)
	v_mfma_f32_16x16x32_bf16 v[108:111], v[198:201], v[166:169], v[108:111]
	v_mfma_f32_16x16x32_bf16 v[104:107], v[206:209], v[166:169], v[104:107]
	v_mfma_f32_16x16x32_bf16 v[92:95], v[198:201], v[174:177], v[92:95]
	v_mfma_f32_16x16x32_bf16 v[88:91], v[206:209], v[174:177], v[88:91]
	v_mfma_f32_16x16x32_bf16 v[76:79], v[198:201], v[182:185], v[76:79]
	v_mfma_f32_16x16x32_bf16 v[72:75], v[206:209], v[182:185], v[72:75]
	v_mfma_f32_16x16x32_bf16 v[68:71], v[198:201], v[190:193], v[68:71]
	v_mfma_f32_16x16x32_bf16 v[64:67], v[206:209], v[190:193], v[64:67]
	v_mfma_f32_16x16x32_bf16 v[108:111], v[202:205], v[170:173], v[108:111]
	v_mfma_f32_16x16x32_bf16 v[104:107], v[214:217], v[170:173], v[104:107]
	v_mfma_f32_16x16x32_bf16 v[92:95], v[202:205], v[178:181], v[92:95]
	v_mfma_f32_16x16x32_bf16 v[88:91], v[214:217], v[178:181], v[88:91]
	v_mfma_f32_16x16x32_bf16 v[76:79], v[202:205], v[186:189], v[76:79]
	v_mfma_f32_16x16x32_bf16 v[72:75], v[214:217], v[186:189], v[72:75]
	v_mfma_f32_16x16x32_bf16 v[68:71], v[202:205], v[194:197], v[68:71]
	v_mfma_f32_16x16x32_bf16 v[64:67], v[214:217], v[194:197], v[64:67]
	s_setprio 0
	s_mov_b32 m0, s46
	v_lshl_add_u64 v[210:211], v[220:221], 0, s[10:11]
	s_barrier
	ds_read_b128 v[166:169], v148 offset:49152
	ds_read_b128 v[170:173], v148 offset:50176
	ds_read_b128 v[174:177], v148 offset:51200
	ds_read_b128 v[178:181], v148 offset:52224
	ds_read_b128 v[182:185], v148 offset:53248
	ds_read_b128 v[186:189], v148 offset:54272
	ds_read_b128 v[190:193], v148 offset:55296
	ds_read_b128 v[194:197], v148 offset:56320
	global_load_lds_dwordx4 v[210:211], off
	v_lshl_add_u64 v[210:211], v[222:223], 0, s[10:11]
	s_mov_b32 m0, s47
	s_nop 0
	global_load_lds_dwordx4 v[210:211], off
	s_barrier
	s_waitcnt lgkmcnt(0)
	s_setprio 1
	s_waitcnt lgkmcnt(0)
	v_mfma_f32_16x16x32_bf16 v[60:63], v[150:153], v[166:169], v[60:63]
	v_mfma_f32_16x16x32_bf16 v[56:59], v[158:161], v[166:169], v[56:59]
	v_mfma_f32_16x16x32_bf16 v[52:55], v[150:153], v[174:177], v[52:55]
	v_mfma_f32_16x16x32_bf16 v[48:51], v[158:161], v[174:177], v[48:51]
	v_mfma_f32_16x16x32_bf16 v[40:43], v[150:153], v[182:185], v[40:43]
	v_mfma_f32_16x16x32_bf16 v[32:35], v[158:161], v[182:185], v[32:35]
	v_mfma_f32_16x16x32_bf16 v[24:27], v[150:153], v[190:193], v[24:27]
	v_mfma_f32_16x16x32_bf16 v[16:19], v[158:161], v[190:193], v[16:19]
	v_mfma_f32_16x16x32_bf16 v[60:63], v[154:157], v[170:173], v[60:63]
	v_mfma_f32_16x16x32_bf16 v[56:59], v[162:165], v[170:173], v[56:59]
	v_mfma_f32_16x16x32_bf16 v[52:55], v[154:157], v[178:181], v[52:55]
	v_mfma_f32_16x16x32_bf16 v[48:51], v[162:165], v[178:181], v[48:51]
	v_mfma_f32_16x16x32_bf16 v[40:43], v[154:157], v[186:189], v[40:43]
	v_mfma_f32_16x16x32_bf16 v[32:35], v[162:165], v[186:189], v[32:35]
	v_mfma_f32_16x16x32_bf16 v[24:27], v[154:157], v[194:197], v[24:27]
	v_mfma_f32_16x16x32_bf16 v[16:19], v[162:165], v[194:197], v[16:19]
	s_setprio 0
	s_barrier
	s_add_u32 s30, s30, 0x40080
	s_addc_u32 s31, s31, 0
	s_add_i32 s34, s34, s41
	v_lshl_add_u64 v[150:151], s[30:31], 0, v[130:131]
	s_mov_b32 m0, s34
	s_nop 0
	global_load_lds_dwordx4 v[150:151], off
	v_lshl_add_u64 v[150:151], s[30:31], 0, v[134:135]
	s_add_i32 m0, s34, 0x2000
	s_nop 0
	global_load_lds_dwordx4 v[150:151], off
	s_waitcnt vmcnt(6)
	s_barrier
	s_setprio 1
	v_mfma_f32_16x16x32_bf16 v[44:47], v[198:201], v[166:169], v[44:47]
	v_mfma_f32_16x16x32_bf16 v[36:39], v[206:209], v[166:169], v[36:39]
	v_mfma_f32_16x16x32_bf16 v[28:31], v[198:201], v[174:177], v[28:31]
	v_mfma_f32_16x16x32_bf16 v[20:23], v[206:209], v[174:177], v[20:23]
	v_mfma_f32_16x16x32_bf16 v[12:15], v[198:201], v[182:185], v[12:15]
	v_mfma_f32_16x16x32_bf16 v[8:11], v[206:209], v[182:185], v[8:11]
	v_mfma_f32_16x16x32_bf16 v[4:7], v[198:201], v[190:193], v[4:7]
	v_mfma_f32_16x16x32_bf16 v[0:3], v[206:209], v[190:193], v[0:3]
	v_mfma_f32_16x16x32_bf16 v[44:47], v[202:205], v[170:173], v[44:47]
	v_mfma_f32_16x16x32_bf16 v[36:39], v[214:217], v[170:173], v[36:39]
	v_mfma_f32_16x16x32_bf16 v[28:31], v[202:205], v[178:181], v[28:31]
	v_mfma_f32_16x16x32_bf16 v[20:23], v[214:217], v[178:181], v[20:23]
	v_mfma_f32_16x16x32_bf16 v[12:15], v[202:205], v[186:189], v[12:15]
	v_mfma_f32_16x16x32_bf16 v[8:11], v[214:217], v[186:189], v[8:11]
	v_mfma_f32_16x16x32_bf16 v[4:7], v[202:205], v[194:197], v[4:7]
	v_mfma_f32_16x16x32_bf16 v[0:3], v[214:217], v[194:197], v[0:3]
	s_setprio 0
	s_add_i32 s60, s60, 2
	s_add_u32 s28, s28, 0x100
	s_addc_u32 s29, s29, 0
	s_add_u32 s58, s58, 0x100
	s_addc_u32 s59, s59, 0
	s_cmp_gt_u32 s60, 13
	s_barrier
